# final RMSNorm and layer-0 deferred-norm row loops rewritten: norm gains hoisted, next row prefetched (double-buffered) with counted vmcnt
# speedup vs baseline: 1.0788x; 1.0060x over previous
; DI int get_bid() { int b = blockIdx.x; LAUNDER_S(b); return b; }
; DI void final_phase(const Params& P, int wv) {
;     ...
;   for (int row = get_bid() * 8 + wave; row < M_LAT; row += gridDim.x * 8) {
;     const float* src = h + (size_t)row * DM;
;     float4 v[4]; float ss = 0.f;
; #pragma unroll
;     for (int i = 0; i < 4; ++i) {
;       v[i] = *(const float4*)(src + i * 256 + lane * 4);
;       ss += v[i].x * v[i].x + v[i].y * v[i].y + v[i].z * v[i].z + v[i].w * v[i].w;
;     }
;     ss = wave_sum(ss, lane);
.LBB0_13:
	global_load_dwordx4 v[60:63], v[6:7], off
	global_load_dwordx4 v[64:67], v[6:7], off offset:1024
	global_load_dwordx4 v[68:71], v[6:7], off offset:2048
	global_load_dwordx4 v[72:75], v[6:7], off offset:3072
	v_readfirstlane_b32 s10, v2
	s_mov_b32 s7, 0
	s_mov_b32 s9, 0
	s_lshl_b32 s6, s10, 12
	v_lshl_add_u64 v[92:93], v[4:5], 0, s[6:7]
	global_load_dwordx4 v[16:19], v[92:93], off
	global_load_dwordx4 v[20:23], v[92:93], off offset:1024
	global_load_dwordx4 v[24:27], v[92:93], off offset:2048
	global_load_dwordx4 v[28:31], v[92:93], off offset:3072
.Lfin_loop:
	s_add_i32 s11, s10, s18
	s_cmp_lt_i32 s11, 0x4000
	s_cbranch_scc0 .Lfin_a_last
	s_lshl_b32 s8, s11, 12
	v_lshl_add_u64 v[94:95], v[4:5], 0, s[8:9]
	global_load_dwordx4 v[76:79], v[94:95], off
	global_load_dwordx4 v[80:83], v[94:95], off offset:1024
	global_load_dwordx4 v[84:87], v[94:95], off offset:2048
	global_load_dwordx4 v[88:91], v[94:95], off offset:3072
	s_waitcnt vmcnt(4)
	s_branch .Lfin_a_go

; DI void final_phase(const Params& P, int wv) {
;     ...
;     for (int i = 0; i < 4; ++i) {
;       v[i] = *(const float4*)(src + i * 256 + lane * 4);
;       ss += v[i].x * v[i].x + v[i].y * v[i].y + v[i].z * v[i].z + v[i].w * v[i].w;
;     }
;     ss = wave_sum(ss, lane);
;     const float r = rsqrtf(ss * (1.f / 1024.f) + 1e-6f);
; #pragma unroll
;     for (int i = 0; i < 4; ++i) {
;       int c = i * 256 + lane * 4;
;       float4 gg = *(const float4*)(P.final_g + c);
;       float4 o = make_float4(v[i].x * r * gg.x, v[i].y * r * gg.y, v[i].z * r * gg.z, v[i].w * r * gg.w);
;       *(float4*)(P.out + (size_t)row * DM + c) = o;
;     }
.Lfin_a_go:
	v_mul_f32_e32 v36, v16, v16
	v_mul_f32_e32 v37, v17, v17
	v_fmac_f32_e32 v36, v18, v18
	v_fmac_f32_e32 v37, v19, v19
	v_fmac_f32_e32 v36, v20, v20
	v_fmac_f32_e32 v37, v21, v21
	v_fmac_f32_e32 v36, v22, v22
	v_fmac_f32_e32 v37, v23, v23
	v_fmac_f32_e32 v36, v24, v24
	v_fmac_f32_e32 v37, v25, v25
	v_fmac_f32_e32 v36, v26, v26
	v_fmac_f32_e32 v37, v27, v27
	v_fmac_f32_e32 v36, v28, v28
	v_fmac_f32_e32 v37, v29, v29
	v_fmac_f32_e32 v36, v30, v30
	v_fmac_f32_e32 v37, v31, v31
	v_add_f32_e32 v0, v36, v37
	ds_bpermute_b32 v3, v10, v0
	s_waitcnt lgkmcnt(0)
	v_add_f32_e32 v0, v0, v3
	ds_bpermute_b32 v3, v11, v0
	s_waitcnt lgkmcnt(0)
	v_add_f32_e32 v0, v0, v3
	ds_bpermute_b32 v3, v12, v0
	s_waitcnt lgkmcnt(0)
	v_add_f32_e32 v0, v0, v3
	ds_bpermute_b32 v3, v13, v0
	s_waitcnt lgkmcnt(0)
	v_add_f32_e32 v0, v0, v3
	ds_bpermute_b32 v3, v14, v0
	s_waitcnt lgkmcnt(0)
	v_add_f32_e32 v0, v0, v3
	ds_bpermute_b32 v3, v15, v0
	s_waitcnt lgkmcnt(0)
	v_add_f32_e32 v0, v0, v3
	v_fmamk_f32 v0, v0, 0x3a800000, v228
	v_mul_f32_e32 v3, 0x4b800000, v0
	v_cmp_gt_f32_e32 vcc, s52, v0
	s_nop 1
	v_cndmask_b32_e32 v0, v0, v3, vcc
	v_rsq_f32_e32 v0, v0
	s_nop 0
	v_mul_f32_e32 v3, 0x45800000, v0
	v_cndmask_b32_e32 v0, v0, v3, vcc
	v_lshl_add_u64 v[96:97], v[8:9], 0, s[6:7]
	v_pk_mul_f32 v[16:17], v[16:17], v[0:1] op_sel_hi:[1,0]
	v_pk_mul_f32 v[18:19], v[18:19], v[0:1] op_sel_hi:[1,0]
	v_pk_mul_f32 v[16:17], v[60:61], v[16:17]
	v_pk_mul_f32 v[18:19], v[62:63], v[18:19]
	global_store_dwordx4 v[96:97], v[16:19], off
	v_pk_mul_f32 v[20:21], v[20:21], v[0:1] op_sel_hi:[1,0]
	v_pk_mul_f32 v[22:23], v[22:23], v[0:1] op_sel_hi:[1,0]
	v_pk_mul_f32 v[20:21], v[64:65], v[20:21]
	v_pk_mul_f32 v[22:23], v[66:67], v[22:23]
	global_store_dwordx4 v[96:97], v[20:23], off offset:1024
	v_pk_mul_f32 v[24:25], v[24:25], v[0:1] op_sel_hi:[1,0]
	v_pk_mul_f32 v[26:27], v[26:27], v[0:1] op_sel_hi:[1,0]
	v_pk_mul_f32 v[24:25], v[68:69], v[24:25]
	v_pk_mul_f32 v[26:27], v[70:71], v[26:27]
	global_store_dwordx4 v[96:97], v[24:27], off offset:2048
	v_pk_mul_f32 v[28:29], v[28:29], v[0:1] op_sel_hi:[1,0]
	v_pk_mul_f32 v[30:31], v[30:31], v[0:1] op_sel_hi:[1,0]
	v_pk_mul_f32 v[28:29], v[72:73], v[28:29]
	v_pk_mul_f32 v[30:31], v[74:75], v[30:31]
	global_store_dwordx4 v[96:97], v[28:31], off offset:3072
	s_cmp_lt_i32 s11, 0x4000
	s_cbranch_scc0 .Lfin_done
	s_add_i32 s10, s11, s18
	s_cmp_lt_i32 s10, 0x4000
	s_cbranch_scc0 .Lfin_b_last
	s_lshl_b32 s6, s10, 12
	v_lshl_add_u64 v[92:93], v[4:5], 0, s[6:7]
	global_load_dwordx4 v[16:19], v[92:93], off
	global_load_dwordx4 v[20:23], v[92:93], off offset:1024
	global_load_dwordx4 v[24:27], v[92:93], off offset:2048
	global_load_dwordx4 v[28:31], v[92:93], off offset:3072
	s_waitcnt vmcnt(4)
	s_branch .Lfin_b_go

; DI void final_phase(const Params& P, int wv) {
;     ...
;     for (int i = 0; i < 4; ++i) {
;       v[i] = *(const float4*)(src + i * 256 + lane * 4);
;       ss += v[i].x * v[i].x + v[i].y * v[i].y + v[i].z * v[i].z + v[i].w * v[i].w;
;     }
;     ss = wave_sum(ss, lane);
;     const float r = rsqrtf(ss * (1.f / 1024.f) + 1e-6f);
; #pragma unroll
;     for (int i = 0; i < 4; ++i) {
;       int c = i * 256 + lane * 4;
;       float4 gg = *(const float4*)(P.final_g + c);
;       float4 o = make_float4(v[i].x * r * gg.x, v[i].y * r * gg.y, v[i].z * r * gg.z, v[i].w * r * gg.w);
;       *(float4*)(P.out + (size_t)row * DM + c) = o;
;     }
.Lfin_b_go:
	v_mul_f32_e32 v36, v76, v76
	v_mul_f32_e32 v37, v77, v77
	v_fmac_f32_e32 v36, v78, v78
	v_fmac_f32_e32 v37, v79, v79
	v_fmac_f32_e32 v36, v80, v80
	v_fmac_f32_e32 v37, v81, v81
	v_fmac_f32_e32 v36, v82, v82
	v_fmac_f32_e32 v37, v83, v83
	v_fmac_f32_e32 v36, v84, v84
	v_fmac_f32_e32 v37, v85, v85
	v_fmac_f32_e32 v36, v86, v86
	v_fmac_f32_e32 v37, v87, v87
	v_fmac_f32_e32 v36, v88, v88
	v_fmac_f32_e32 v37, v89, v89
	v_fmac_f32_e32 v36, v90, v90
	v_fmac_f32_e32 v37, v91, v91
	v_add_f32_e32 v0, v36, v37
	ds_bpermute_b32 v3, v10, v0
	s_waitcnt lgkmcnt(0)
	v_add_f32_e32 v0, v0, v3
	ds_bpermute_b32 v3, v11, v0
	s_waitcnt lgkmcnt(0)
	v_add_f32_e32 v0, v0, v3
	ds_bpermute_b32 v3, v12, v0
	s_waitcnt lgkmcnt(0)
	v_add_f32_e32 v0, v0, v3
	ds_bpermute_b32 v3, v13, v0
	s_waitcnt lgkmcnt(0)
	v_add_f32_e32 v0, v0, v3
	ds_bpermute_b32 v3, v14, v0
	s_waitcnt lgkmcnt(0)
	v_add_f32_e32 v0, v0, v3
	ds_bpermute_b32 v3, v15, v0
	s_waitcnt lgkmcnt(0)
	v_add_f32_e32 v0, v0, v3
	v_fmamk_f32 v0, v0, 0x3a800000, v228
	v_mul_f32_e32 v3, 0x4b800000, v0
	v_cmp_gt_f32_e32 vcc, s52, v0
	s_nop 1
	v_cndmask_b32_e32 v0, v0, v3, vcc
	v_rsq_f32_e32 v0, v0
	s_nop 0
	v_mul_f32_e32 v3, 0x45800000, v0
	v_cndmask_b32_e32 v0, v0, v3, vcc
	v_lshl_add_u64 v[96:97], v[8:9], 0, s[8:9]
	v_pk_mul_f32 v[76:77], v[76:77], v[0:1] op_sel_hi:[1,0]
	v_pk_mul_f32 v[78:79], v[78:79], v[0:1] op_sel_hi:[1,0]
	v_pk_mul_f32 v[76:77], v[60:61], v[76:77]
	v_pk_mul_f32 v[78:79], v[62:63], v[78:79]
	global_store_dwordx4 v[96:97], v[76:79], off
	v_pk_mul_f32 v[80:81], v[80:81], v[0:1] op_sel_hi:[1,0]
	v_pk_mul_f32 v[82:83], v[82:83], v[0:1] op_sel_hi:[1,0]
	v_pk_mul_f32 v[80:81], v[64:65], v[80:81]
	v_pk_mul_f32 v[82:83], v[66:67], v[82:83]
	global_store_dwordx4 v[96:97], v[80:83], off offset:1024
	v_pk_mul_f32 v[84:85], v[84:85], v[0:1] op_sel_hi:[1,0]
	v_pk_mul_f32 v[86:87], v[86:87], v[0:1] op_sel_hi:[1,0]
	v_pk_mul_f32 v[84:85], v[68:69], v[84:85]
	v_pk_mul_f32 v[86:87], v[70:71], v[86:87]
	global_store_dwordx4 v[96:97], v[84:87], off offset:2048
	v_pk_mul_f32 v[88:89], v[88:89], v[0:1] op_sel_hi:[1,0]
	v_pk_mul_f32 v[90:91], v[90:91], v[0:1] op_sel_hi:[1,0]
	v_pk_mul_f32 v[88:89], v[72:73], v[88:89]
	v_pk_mul_f32 v[90:91], v[74:75], v[90:91]
	global_store_dwordx4 v[96:97], v[88:91], off offset:3072
	s_cmp_lt_i32 s10, 0x4000
	s_cbranch_scc1 .Lfin_loop
.Lfin_done:
	v_readlane_b32 s6, v254, 4
	v_readlane_b32 s7, v254, 5
	v_readlane_b32 s8, v254, 6
	v_readlane_b32 s9, v254, 7
	v_readlane_b32 s10, v254, 8
	v_readlane_b32 s11, v254, 9

; DI unsigned pk2(float a, float b) { f2_t v = {a, b}; bf2_t r = __builtin_convertvector(v, bf2_t); return __builtin_bit_cast(unsigned, r); }
; DI void phase0b(const Params& P, unsigned char* lds, int wv) {
;     ...
;   for (int row = bid * 8 + wave; row < M_ALL; row += G * 8) {
;     const float* src = row < M_LAT ? P.x + (size_t)row * DM : P.ctx + (size_t)(row - M_LAT) * DM;
;     const int bi = row < M_LAT ? (row >> 11) : 8;
;     const float* sc = mod + bi * NMOD + 1024;
;     float ss = 0.f;
; #pragma unroll
;     for (int i = 0; i < 4; ++i) {
;       const int c = i * 256 + lane * 4;
;       const float4 v = *(const float4*)(src + c);
;       ss += v.x * v.x + v.y * v.y + v.z * v.z + v.w * v.w;
;       const float4 gg = *(const float4*)(P.norm_g + c), s4 = *(const float4*)(sc + c);
;       u32x2 o; o[0] = pk2(v.x * gg.x * (1.f + s4.x), v.y * gg.y * (1.f + s4.y)); o[1] = pk2(v.z * gg.z * (1.f + s4.z), v.w * gg.w * (1.f + s4.w));
;       *(u32x2*)(hg + (size_t)row * DM + c) = o;
.LBB0_53:
	v_ashrrev_i32_e32 v0, 6, v47
	s_nop 1
	v_lshl_add_u32 v6, s12, 3, v0
	s_movk_i32 s0, 0x4800
	v_cmp_gt_i32_e32 vcc, s0, v6
	s_and_saveexec_b64 s[4:5], vcc
	s_cbranch_execz .LBB0_63
	v_readlane_b32 s0, v254, 45
	v_readlane_b32 s1, v254, 46
	s_add_u32 s6, s0, 0x18798000
	s_waitcnt lgkmcnt(0)
	v_and_b32_e32 v3, 63, v47
	s_addc_u32 s7, s1, 0
	v_lshlrev_b32_e32 v0, 4, v3
	v_lshlrev_b32_e32 v2, 2, v3
	s_add_u32 s8, s0, 0x187e0000
	v_lshl_add_u64 v[8:9], s[84:85], 0, v[0:1]
	v_lshlrev_b32_e32 v0, 3, v3
	v_ashrrev_i32_e32 v7, 31, v6
	s_addc_u32 s9, s1, 0
	v_or_b32_e32 v4, 0x100, v2
	v_or_b32_e32 v16, 0x200, v2
	v_or_b32_e32 v18, 0x300, v2
	v_lshl_add_u64 v[10:11], s[0:1], 0, v[0:1]
	s_mov_b64 s[0:1], 0xe346000
	v_lshlrev_b64 v[12:13], 12, v[6:7]
	v_xor_b32_e32 v20, 0x80, v2
	v_xor_b32_e32 v21, 64, v2
	v_xor_b32_e32 v22, 32, v2
	v_xor_b32_e32 v23, 16, v2
	v_xor_b32_e32 v24, 8, v2
	v_xor_b32_e32 v25, 4, v2
	v_cmp_eq_u32_e32 vcc, 0, v3
	v_lshl_add_u64 v[10:11], v[10:11], 0, s[0:1]
	v_lshl_add_u64 v[12:13], s[72:73], 0, v[12:13]
	s_mov_b64 s[10:11], 0
	v_lshlrev_b32_e32 v0, 2, v2
	v_lshlrev_b32_e32 v14, 2, v4
	v_lshlrev_b32_e32 v16, 2, v16
	v_lshlrev_b32_e32 v18, 2, v18
	global_load_dwordx4 v[60:63], v[8:9], off
	global_load_dwordx4 v[64:67], v[8:9], off offset:1024
	global_load_dwordx4 v[68:71], v[8:9], off offset:2048
	global_load_dwordx4 v[72:75], v[8:9], off offset:3072
	v_readfirstlane_b32 s10, v6
	v_lshrrev_b32_e32 v52, 1, v0
	v_readlane_b32 s100, v254, 45
	v_readlane_b32 s101, v254, 46
	s_add_u32 s100, s100, 0x3000
	s_addc_u32 s101, s101, 0
	s_add_i32 s0, s10, 0xffffc000
	s_min_u32 s1, s10, 0x4000
	s_lshr_b32 s1, s1, 11
	s_mul_i32 s1, s1, 0x9000
	s_cmp_lt_u32 s10, 0x4000
	s_cselect_b32 s12, s72, s76
	s_cselect_b32 s13, s73, s77
	s_cselect_b32 s0, s10, s0
	s_lshl_b32 s0, s0, 12
	s_add_u32 s12, s12, s0
	s_addc_u32 s13, s13, 0
	s_add_u32 s14, s100, s1
	s_addc_u32 s15, s101, 0
	global_load_dwordx4 v[76:79], v0, s[12:13]
	global_load_dwordx4 v[80:83], v0, s[12:13] offset:1024
	global_load_dwordx4 v[84:87], v0, s[12:13] offset:2048
	global_load_dwordx4 v[88:91], v0, s[12:13] offset:3072
	global_load_dwordx4 v[92:95], v0, s[14:15]
	global_load_dwordx4 v[96:99], v0, s[14:15] offset:1024
	global_load_dwordx4 v[100:103], v0, s[14:15] offset:2048
	global_load_dwordx4 v[104:107], v0, s[14:15] offset:3072
.Lp0b_loop:
	s_add_i32 s11, s10, s18
	s_cmp_lt_u32 s11, 0x4800
	s_cbranch_scc0 .Lp0b_a_last
	s_add_i32 s0, s11, 0xffffc000
	s_min_u32 s1, s11, 0x4000
	s_lshr_b32 s1, s1, 11
	s_mul_i32 s1, s1, 0x9000
	s_cmp_lt_u32 s11, 0x4000
	s_cselect_b32 s12, s72, s76
	s_cselect_b32 s13, s73, s77
	s_cselect_b32 s0, s11, s0
	s_lshl_b32 s0, s0, 12
	s_add_u32 s12, s12, s0
	s_addc_u32 s13, s13, 0
	s_add_u32 s14, s100, s1
	s_addc_u32 s15, s101, 0
	global_load_dwordx4 v[108:111], v0, s[12:13]
	global_load_dwordx4 v[112:115], v0, s[12:13] offset:1024
	global_load_dwordx4 v[116:119], v0, s[12:13] offset:2048
	global_load_dwordx4 v[120:123], v0, s[12:13] offset:3072
	global_load_dwordx4 v[124:127], v0, s[14:15]
	global_load_dwordx4 v[128:131], v0, s[14:15] offset:1024
	global_load_dwordx4 v[132:135], v0, s[14:15] offset:2048
	global_load_dwordx4 v[136:139], v0, s[14:15] offset:3072
	s_waitcnt vmcnt(8)
	s_branch .Lp0b_a_go

; DI unsigned pk2(float a, float b) { f2_t v = {a, b}; bf2_t r = __builtin_convertvector(v, bf2_t); return __builtin_bit_cast(unsigned, r); }
; DI void phase0b(const Params& P, unsigned char* lds, int wv) {
;     ...
;     const float* src = row < M_LAT ? P.x + (size_t)row * DM : P.ctx + (size_t)(row - M_LAT) * DM;
;     const int bi = row < M_LAT ? (row >> 11) : 8;
;     const float* sc = mod + bi * NMOD + 1024;
;     float ss = 0.f;
; #pragma unroll
;     for (int i = 0; i < 4; ++i) {
;       const int c = i * 256 + lane * 4;
;       const float4 v = *(const float4*)(src + c);
;       ss += v.x * v.x + v.y * v.y + v.z * v.z + v.w * v.w;
;       const float4 gg = *(const float4*)(P.norm_g + c), s4 = *(const float4*)(sc + c);
;       u32x2 o; o[0] = pk2(v.x * gg.x * (1.f + s4.x), v.y * gg.y * (1.f + s4.y)); o[1] = pk2(v.z * gg.z * (1.f + s4.z), v.w * gg.w * (1.f + s4.w));
;       *(u32x2*)(hg + (size_t)row * DM + c) = o;
;     }
;     ss = wave_sum(ss, lane);
;     if (lane == 0) {
;       const float z = ss * 0.f;
;       if (row < M_LAT) *(float4*)(ssp + (size_t)row * 4) = make_float4(ss, z, z, z);
;       else { float* q_ = ssp + (size_t)M_ALL * 4 + (size_t)(row - M_LAT) * 8; *(float4*)q_ = make_float4(ss, z, z, z); *(float4*)(q_ + 4) = make_float4(z, z, z, z); }
;     }
.Lp0b_a_go:
	v_mul_f32_e32 v2, v76, v76
	v_mul_f32_e32 v3, v77, v77
	v_fmac_f32_e32 v2, v78, v78
	v_fmac_f32_e32 v3, v79, v79
	v_fmac_f32_e32 v2, v80, v80
	v_fmac_f32_e32 v3, v81, v81
	v_fmac_f32_e32 v2, v82, v82
	v_fmac_f32_e32 v3, v83, v83
	v_fmac_f32_e32 v2, v84, v84
	v_fmac_f32_e32 v3, v85, v85
	v_fmac_f32_e32 v2, v86, v86
	v_fmac_f32_e32 v3, v87, v87
	v_fmac_f32_e32 v2, v88, v88
	v_fmac_f32_e32 v3, v89, v89
	v_fmac_f32_e32 v2, v90, v90
	v_fmac_f32_e32 v3, v91, v91
	v_add_f32_e32 v2, v2, v3
	v_readlane_b32 s12, v254, 45
	v_readlane_b32 s13, v254, 46
	s_lshl_b32 s0, s10, 11
	s_add_u32 s12, s12, 0xe346000
	s_addc_u32 s13, s13, 0
	s_add_u32 s12, s12, s0
	s_addc_u32 s13, s13, 0
	v_pk_mul_f32 v[76:77], v[76:77], v[60:61]
	v_pk_mul_f32 v[78:79], v[78:79], v[62:63]
	v_pk_add_f32 v[92:93], v[92:93], 1.0 op_sel_hi:[1,0]
	v_pk_add_f32 v[94:95], v[94:95], 1.0 op_sel_hi:[1,0]
	v_pk_mul_f32 v[76:77], v[76:77], v[92:93]
	v_pk_mul_f32 v[78:79], v[78:79], v[94:95]
	v_cvt_pk_bf16_f32 v26, v76, v77
	v_cvt_pk_bf16_f32 v27, v78, v79
	global_store_dwordx2 v52, v[26:27], s[12:13]
	v_pk_mul_f32 v[80:81], v[80:81], v[64:65]
	v_pk_mul_f32 v[82:83], v[82:83], v[66:67]
	v_pk_add_f32 v[96:97], v[96:97], 1.0 op_sel_hi:[1,0]
	v_pk_add_f32 v[98:99], v[98:99], 1.0 op_sel_hi:[1,0]
	v_pk_mul_f32 v[80:81], v[80:81], v[96:97]
	v_pk_mul_f32 v[82:83], v[82:83], v[98:99]
	v_cvt_pk_bf16_f32 v28, v80, v81
	v_cvt_pk_bf16_f32 v29, v82, v83
	global_store_dwordx2 v52, v[28:29], s[12:13] offset:512
	v_pk_mul_f32 v[84:85], v[84:85], v[68:69]
	v_pk_mul_f32 v[86:87], v[86:87], v[70:71]
	v_pk_add_f32 v[100:101], v[100:101], 1.0 op_sel_hi:[1,0]
	v_pk_add_f32 v[102:103], v[102:103], 1.0 op_sel_hi:[1,0]
	v_pk_mul_f32 v[84:85], v[84:85], v[100:101]
	v_pk_mul_f32 v[86:87], v[86:87], v[102:103]
	v_cvt_pk_bf16_f32 v30, v84, v85
	v_cvt_pk_bf16_f32 v31, v86, v87
	global_store_dwordx2 v52, v[30:31], s[12:13] offset:1024
	v_pk_mul_f32 v[88:89], v[88:89], v[72:73]
	v_pk_mul_f32 v[90:91], v[90:91], v[74:75]
	v_pk_add_f32 v[104:105], v[104:105], 1.0 op_sel_hi:[1,0]
	v_pk_add_f32 v[106:107], v[106:107], 1.0 op_sel_hi:[1,0]
	v_pk_mul_f32 v[88:89], v[88:89], v[104:105]
	v_pk_mul_f32 v[90:91], v[90:91], v[106:107]
	v_cvt_pk_bf16_f32 v32, v88, v89
	v_cvt_pk_bf16_f32 v33, v90, v91
	global_store_dwordx2 v52, v[32:33], s[12:13] offset:1536
	ds_bpermute_b32 v3, v20, v2
	s_waitcnt lgkmcnt(0)
	v_add_f32_e32 v2, v2, v3
	ds_bpermute_b32 v3, v21, v2
	s_waitcnt lgkmcnt(0)
	v_add_f32_e32 v2, v2, v3
	ds_bpermute_b32 v3, v22, v2
	s_waitcnt lgkmcnt(0)
	v_add_f32_e32 v2, v2, v3
	ds_bpermute_b32 v3, v23, v2
	s_waitcnt lgkmcnt(0)
	v_add_f32_e32 v2, v2, v3
	ds_bpermute_b32 v3, v24, v2
	s_waitcnt lgkmcnt(0)
	v_add_f32_e32 v2, v2, v3
	ds_bpermute_b32 v3, v25, v2
	s_waitcnt lgkmcnt(0)
	v_add_f32_e32 v2, v2, v3
	v_mul_f32_e32 v3, 0, v2
	v_mov_b32_e32 v4, v3
	v_mov_b32_e32 v5, v3
	v_mov_b32_e32 v34, v3
	v_mov_b32_e32 v35, v3
	v_mov_b32_e32 v36, v3
	v_mov_b32_e32 v37, v3
	s_and_saveexec_b64 s[14:15], vcc
	s_cmp_lt_u32 s10, 0x4000
	s_cbranch_scc0 .Lp0b_ctx_a
	s_lshl_b32 s0, s10, 4
	s_add_u32 s0, s6, s0
	s_addc_u32 s1, s7, 0
	s_nop 0
	global_store_dwordx4 v1, v[2:5], s[0:1]
	s_branch .Lp0b_st_a
.Lp0b_ctx_a:
	s_add_i32 s0, s10, 0xffffc000
	s_lshl_b32 s0, s0, 5
	s_add_u32 s0, s8, s0
	s_addc_u32 s1, s9, 0
	s_nop 0
	global_store_dwordx4 v1, v[2:5], s[0:1]
	global_store_dwordx4 v1, v[34:37], s[0:1] offset:16
.Lp0b_st_a:
	s_mov_b64 exec, s[14:15]
	s_cmp_lt_u32 s11, 0x4800
	s_cbranch_scc0 .Lp0b_done
	s_add_i32 s10, s11, s18
	s_cmp_lt_u32 s10, 0x4800
	s_cbranch_scc0 .Lp0b_b_last
	s_add_i32 s0, s10, 0xffffc000
	s_min_u32 s1, s10, 0x4000
	s_lshr_b32 s1, s1, 11
	s_mul_i32 s1, s1, 0x9000
	s_cmp_lt_u32 s10, 0x4000
	s_cselect_b32 s12, s72, s76
	s_cselect_b32 s13, s73, s77
	s_cselect_b32 s0, s10, s0
	s_lshl_b32 s0, s0, 12
	s_add_u32 s12, s12, s0
	s_addc_u32 s13, s13, 0
	s_add_u32 s14, s100, s1
	s_addc_u32 s15, s101, 0
	global_load_dwordx4 v[76:79], v0, s[12:13]
	global_load_dwordx4 v[80:83], v0, s[12:13] offset:1024
	global_load_dwordx4 v[84:87], v0, s[12:13] offset:2048
	global_load_dwordx4 v[88:91], v0, s[12:13] offset:3072
	global_load_dwordx4 v[92:95], v0, s[14:15]
	global_load_dwordx4 v[96:99], v0, s[14:15] offset:1024
	global_load_dwordx4 v[100:103], v0, s[14:15] offset:2048
	global_load_dwordx4 v[104:107], v0, s[14:15] offset:3072
	s_waitcnt vmcnt(8)
	s_branch .Lp0b_b_go

; DI unsigned pk2(float a, float b) { f2_t v = {a, b}; bf2_t r = __builtin_convertvector(v, bf2_t); return __builtin_bit_cast(unsigned, r); }
; DI void phase0b(const Params& P, unsigned char* lds, int wv) {
;     ...
;     for (int i = 0; i < 4; ++i) {
;       const int c = i * 256 + lane * 4;
;       const float4 v = *(const float4*)(src + c);
;       ss += v.x * v.x + v.y * v.y + v.z * v.z + v.w * v.w;
;       const float4 gg = *(const float4*)(P.norm_g + c), s4 = *(const float4*)(sc + c);
;       u32x2 o; o[0] = pk2(v.x * gg.x * (1.f + s4.x), v.y * gg.y * (1.f + s4.y)); o[1] = pk2(v.z * gg.z * (1.f + s4.z), v.w * gg.w * (1.f + s4.w));
;       *(u32x2*)(hg + (size_t)row * DM + c) = o;
;     }
;     ss = wave_sum(ss, lane);
;     if (lane == 0) {
;       const float z = ss * 0.f;
;       if (row < M_LAT) *(float4*)(ssp + (size_t)row * 4) = make_float4(ss, z, z, z);
;       else { float* q_ = ssp + (size_t)M_ALL * 4 + (size_t)(row - M_LAT) * 8; *(float4*)q_ = make_float4(ss, z, z, z); *(float4*)(q_ + 4) = make_float4(z, z, z, z); }
;     }
.Lp0b_b_go:
	v_mul_f32_e32 v2, v108, v108
	v_mul_f32_e32 v3, v109, v109
	v_fmac_f32_e32 v2, v110, v110
	v_fmac_f32_e32 v3, v111, v111
	v_fmac_f32_e32 v2, v112, v112
	v_fmac_f32_e32 v3, v113, v113
	v_fmac_f32_e32 v2, v114, v114
	v_fmac_f32_e32 v3, v115, v115
	v_fmac_f32_e32 v2, v116, v116
	v_fmac_f32_e32 v3, v117, v117
	v_fmac_f32_e32 v2, v118, v118
	v_fmac_f32_e32 v3, v119, v119
	v_fmac_f32_e32 v2, v120, v120
	v_fmac_f32_e32 v3, v121, v121
	v_fmac_f32_e32 v2, v122, v122
	v_fmac_f32_e32 v3, v123, v123
	v_add_f32_e32 v2, v2, v3
	v_readlane_b32 s12, v254, 45
	v_readlane_b32 s13, v254, 46
	s_lshl_b32 s0, s11, 11
	s_add_u32 s12, s12, 0xe346000
	s_addc_u32 s13, s13, 0
	s_add_u32 s12, s12, s0
	s_addc_u32 s13, s13, 0
	v_pk_mul_f32 v[108:109], v[108:109], v[60:61]
	v_pk_mul_f32 v[110:111], v[110:111], v[62:63]
	v_pk_add_f32 v[124:125], v[124:125], 1.0 op_sel_hi:[1,0]
	v_pk_add_f32 v[126:127], v[126:127], 1.0 op_sel_hi:[1,0]
	v_pk_mul_f32 v[108:109], v[108:109], v[124:125]
	v_pk_mul_f32 v[110:111], v[110:111], v[126:127]
	v_cvt_pk_bf16_f32 v26, v108, v109
	v_cvt_pk_bf16_f32 v27, v110, v111
	global_store_dwordx2 v52, v[26:27], s[12:13]
	v_pk_mul_f32 v[112:113], v[112:113], v[64:65]
	v_pk_mul_f32 v[114:115], v[114:115], v[66:67]
	v_pk_add_f32 v[128:129], v[128:129], 1.0 op_sel_hi:[1,0]
	v_pk_add_f32 v[130:131], v[130:131], 1.0 op_sel_hi:[1,0]
	v_pk_mul_f32 v[112:113], v[112:113], v[128:129]
	v_pk_mul_f32 v[114:115], v[114:115], v[130:131]
	v_cvt_pk_bf16_f32 v28, v112, v113
	v_cvt_pk_bf16_f32 v29, v114, v115
	global_store_dwordx2 v52, v[28:29], s[12:13] offset:512
	v_pk_mul_f32 v[116:117], v[116:117], v[68:69]
	v_pk_mul_f32 v[118:119], v[118:119], v[70:71]
	v_pk_add_f32 v[132:133], v[132:133], 1.0 op_sel_hi:[1,0]
	v_pk_add_f32 v[134:135], v[134:135], 1.0 op_sel_hi:[1,0]
	v_pk_mul_f32 v[116:117], v[116:117], v[132:133]
	v_pk_mul_f32 v[118:119], v[118:119], v[134:135]
	v_cvt_pk_bf16_f32 v30, v116, v117
	v_cvt_pk_bf16_f32 v31, v118, v119
	global_store_dwordx2 v52, v[30:31], s[12:13] offset:1024
	v_pk_mul_f32 v[120:121], v[120:121], v[72:73]
	v_pk_mul_f32 v[122:123], v[122:123], v[74:75]
	v_pk_add_f32 v[136:137], v[136:137], 1.0 op_sel_hi:[1,0]
	v_pk_add_f32 v[138:139], v[138:139], 1.0 op_sel_hi:[1,0]
	v_pk_mul_f32 v[120:121], v[120:121], v[136:137]
	v_pk_mul_f32 v[122:123], v[122:123], v[138:139]
	v_cvt_pk_bf16_f32 v32, v120, v121
	v_cvt_pk_bf16_f32 v33, v122, v123
	global_store_dwordx2 v52, v[32:33], s[12:13] offset:1536
	ds_bpermute_b32 v3, v20, v2
	s_waitcnt lgkmcnt(0)
	v_add_f32_e32 v2, v2, v3
	ds_bpermute_b32 v3, v21, v2
	s_waitcnt lgkmcnt(0)
	v_add_f32_e32 v2, v2, v3
	ds_bpermute_b32 v3, v22, v2
	s_waitcnt lgkmcnt(0)
	v_add_f32_e32 v2, v2, v3
	ds_bpermute_b32 v3, v23, v2
	s_waitcnt lgkmcnt(0)
	v_add_f32_e32 v2, v2, v3
	ds_bpermute_b32 v3, v24, v2
	s_waitcnt lgkmcnt(0)
	v_add_f32_e32 v2, v2, v3
	ds_bpermute_b32 v3, v25, v2
	s_waitcnt lgkmcnt(0)
	v_add_f32_e32 v2, v2, v3
	v_mul_f32_e32 v3, 0, v2
	v_mov_b32_e32 v4, v3
	v_mov_b32_e32 v5, v3
	v_mov_b32_e32 v34, v3
	v_mov_b32_e32 v35, v3
	v_mov_b32_e32 v36, v3
	v_mov_b32_e32 v37, v3
	s_and_saveexec_b64 s[14:15], vcc
	s_cmp_lt_u32 s11, 0x4000
	s_cbranch_scc0 .Lp0b_ctx_b
	s_lshl_b32 s0, s11, 4
	s_add_u32 s0, s6, s0
	s_addc_u32 s1, s7, 0
	s_nop 0
	global_store_dwordx4 v1, v[2:5], s[0:1]
	s_branch .Lp0b_st_b
.Lp0b_ctx_b:
	s_add_i32 s0, s11, 0xffffc000
	s_lshl_b32 s0, s0, 5
	s_add_u32 s0, s8, s0
	s_addc_u32 s1, s9, 0
	s_nop 0
	global_store_dwordx4 v1, v[2:5], s[0:1]
	global_store_dwordx4 v1, v[34:37], s[0:1] offset:16
.Lp0b_st_b:
	s_mov_b64 exec, s[14:15]
	s_cmp_lt_u32 s10, 0x4800
	s_cbranch_scc1 .Lp0b_loop
.Lp0b_done:
.LBB0_63:
	s_or_b64 exec, exec, s[4:5]
	s_mov_b64 s[0:1], 0
